# v22 + stick-breaking: 107 canonicalize+min pairs fused (dependency-aware hazard check)
# speedup vs baseline: 1.0105x; 1.0046x over previous
.LBB0_426:
	s_bitcmp1_b32 s22, 0
	s_cselect_b32 s23, 0x2080, 0
	v_add_u32_e32 v77, s23, v196
	ds_read_b128 v[0:3], v77
	ds_read_b128 v[16:19], v229 offset:60416
	s_and_b32 s16, s39, 1
	s_mul_i32 s17, s16, 0x2080
	v_min_f32_e64 v4, -v32, s98
	v_exp_f32_e32 v24, v4
	v_min_f32_e64 v26, -v33, s98
	v_exp_f32_e32 v26, v26
	v_add_f32_e32 v25, 1.0, v24
	v_rcp_f32_e32 v25, v25
	v_or_b32_e32 v75, s4, v197
	v_cmp_lt_i32_e32 vcc, v75, v72
	v_or_b32_e32 v27, 1, v75
	v_mul_f32_e32 v24, v24, v25
	v_cndmask_b32_e32 v32, 0, v25, vcc
	v_cndmask_b32_e32 v24, 1.0, v24, vcc
	v_cmp_lt_i32_e32 vcc, v27, v72
	v_max_f32_e64 v27, -v34, -v34
	v_add_f32_e32 v25, 1.0, v26
	v_min_f32_e32 v27, 0x42700000, v27
	v_rcp_f32_e32 v25, v25
	v_exp_f32_e32 v27, v27
	v_max_f32_e64 v28, -v35, -v35
	v_min_f32_e32 v28, 0x42700000, v28
	v_cndmask_b32_e32 v33, 0, v25, vcc
	v_mul_f32_e32 v25, v26, v25
	v_add_f32_e32 v26, 1.0, v27
	v_rcp_f32_e32 v26, v26
	v_exp_f32_e32 v28, v28
	v_cndmask_b32_e32 v73, 1.0, v25, vcc
	v_or_b32_e32 v25, 2, v75
	v_cmp_lt_i32_e32 vcc, v25, v72
	s_waitcnt lgkmcnt(0)
	v_mfma_f32_32x32x16_bf16 v[0:15], v[0:3], v[16:19], 0
	v_mul_f32_e32 v25, v27, v26
	v_cndmask_b32_e32 v34, 0, v26, vcc
	v_add_f32_e32 v26, 1.0, v28
	v_rcp_f32_e32 v26, v26
	ds_read_b128 v[20:23], v77 offset:512
	v_cndmask_b32_e32 v107, 1.0, v25, vcc
	v_or_b32_e32 v25, 3, v75
	v_cmp_lt_i32_e32 vcc, v25, v72
	v_mul_f32_e32 v25, v28, v26
	v_mul_f32_e32 v24, v24, v73
	v_cndmask_b32_e32 v108, 1.0, v25, vcc
	v_cndmask_b32_e32 v35, 0, v26, vcc
	v_mul_f32_e32 v25, v107, v108
	v_mul_f32_e32 v106, v24, v25
	v_or_b32_e32 v74, 8, v75
	v_min_f32_e64 v36, -v36, s98
	v_cmp_lt_i32_e32 vcc, v74, v72
	v_exp_f32_e32 v74, v36
	v_max_f32_e64 v37, -v37, -v37
	v_min_f32_e32 v37, 0x42700000, v37
	v_min_f32_e64 v38, -v38, s98
	v_add_f32_e32 v36, 1.0, v74
	v_rcp_f32_e32 v76, v36
	v_max_f32_e64 v39, -v39, -v39
	v_min_f32_e32 v39, 0x42700000, v39
	v_cndmask_b32_e32 v36, 0, v76, vcc
	v_mul_f32_e32 v74, v74, v76
	v_or_b32_e32 v76, 9, v75
	v_cndmask_b32_e32 v74, 1.0, v74, vcc
	v_cmp_lt_i32_e32 vcc, v76, v72
	v_exp_f32_e32 v76, v37
	s_waitcnt lgkmcnt(0)
	v_mfma_f32_32x32x16_bf16 v[16:31], v[20:23], v[16:19], 0
	ds_read_b128 v[68:71], v77 offset:2080
	ds_read_b128 v[64:67], v229 offset:61440
	v_add_f32_e32 v37, 1.0, v76
	v_rcp_f32_e32 v78, v37
	s_nop 0
	v_mul_f32_e32 v76, v76, v78
	v_cndmask_b32_e32 v109, 1.0, v76, vcc
	v_or_b32_e32 v76, 10, v75
	v_cndmask_b32_e32 v37, 0, v78, vcc
	v_cmp_lt_i32_e32 vcc, v76, v72
	v_exp_f32_e32 v76, v38
	v_mul_f32_e32 v74, v74, v109
	v_add_f32_e32 v38, 1.0, v76
	v_rcp_f32_e32 v78, v38
	s_nop 0
	v_mul_f32_e32 v76, v76, v78
	v_cndmask_b32_e32 v110, 1.0, v76, vcc
	v_or_b32_e32 v76, 11, v75
	v_cndmask_b32_e32 v38, 0, v78, vcc
	v_cmp_lt_i32_e32 vcc, v76, v72
	v_exp_f32_e32 v76, v39
	s_nop 0
	v_add_f32_e32 v39, 1.0, v76
	v_rcp_f32_e32 v78, v39
	s_nop 0
	v_mul_f32_e32 v76, v76, v78
	v_cndmask_b32_e32 v111, 1.0, v76, vcc
	v_mul_f32_e32 v76, v110, v111
	v_cndmask_b32_e32 v39, 0, v78, vcc
	v_mul_f32_e32 v74, v74, v76
	v_min_f32_e64 v40, -v40, s98
	v_exp_f32_e32 v76, v40
	v_min_f32_e64 v41, -v41, s98
	s_waitcnt lgkmcnt(0)
	v_mfma_f32_32x32x16_bf16 v[0:15], v[68:71], v[64:67], v[0:15]
	v_add_f32_e32 v82, 1.0, v76
	v_rcp_f32_e32 v68, v82
	v_exp_f32_e32 v69, v41
	v_or_b32_e32 v40, 16, v75
	v_cmp_lt_i32_e32 vcc, v40, v72
	v_max_f32_e64 v42, -v42, -v42
	v_mul_f32_e32 v41, v76, v68
	v_cndmask_b32_e32 v40, 0, v68, vcc
	v_add_f32_e32 v68, 1.0, v69
	v_min_f32_e32 v42, 0x42700000, v42
	v_rcp_f32_e32 v68, v68
	v_exp_f32_e32 v71, v42
	v_cndmask_b32_e32 v70, 1.0, v41, vcc
	v_or_b32_e32 v41, 17, v75
	v_cmp_lt_i32_e32 vcc, v41, v72
	v_max_f32_e64 v43, -v43, -v43
	v_mul_f32_e32 v42, v69, v68
	v_cndmask_b32_e32 v41, 0, v68, vcc
	v_add_f32_e32 v68, 1.0, v71
	v_min_f32_e32 v43, 0x42700000, v43
	v_rcp_f32_e32 v68, v68
	v_exp_f32_e32 v69, v43
	v_cndmask_b32_e32 v112, 1.0, v42, vcc
	v_or_b32_e32 v42, 18, v75
	v_cmp_lt_i32_e32 vcc, v42, v72
	v_mul_f32_e32 v43, v71, v68
	ds_read_b128 v[78:81], v77 offset:2592
	v_cndmask_b32_e32 v42, 0, v68, vcc
	v_add_f32_e32 v68, 1.0, v69
	v_rcp_f32_e32 v68, v68
	v_cndmask_b32_e32 v113, 1.0, v43, vcc
	v_or_b32_e32 v43, 19, v75
	v_cmp_lt_i32_e32 vcc, v43, v72
	s_nop 1
	v_cndmask_b32_e32 v43, 0, v68, vcc
	v_mul_f32_e32 v68, v69, v68
	v_cndmask_b32_e32 v114, 1.0, v68, vcc
	v_mul_f32_e32 v68, v70, v112
	v_mul_f32_e32 v69, v113, v114
	v_mul_f32_e32 v76, v68, v69
	v_min_f32_e64 v44, -v44, s98
	s_waitcnt lgkmcnt(0)
	v_mfma_f32_32x32x16_bf16 v[16:31], v[78:81], v[64:67], v[16:31]
	v_or_b32_e32 v64, 24, v75
	v_cmp_lt_i32_e32 vcc, v64, v72
	v_exp_f32_e32 v64, v44
	v_max_f32_e64 v45, -v45, -v45
	v_min_f32_e32 v45, 0x42700000, v45
	v_min_f32_e64 v46, -v46, s98
	v_add_f32_e32 v44, 1.0, v64
	v_rcp_f32_e32 v65, v44
	v_max_f32_e64 v47, -v47, -v47
	v_min_f32_e32 v47, 0x42700000, v47
	v_cndmask_b32_e32 v44, 0, v65, vcc
	v_mul_f32_e32 v64, v64, v65
	v_or_b32_e32 v65, 25, v75
	v_cndmask_b32_e32 v64, 1.0, v64, vcc
	v_cmp_lt_i32_e32 vcc, v65, v72
	v_exp_f32_e32 v65, v45
	ds_read_b128 v[82:85], v77 offset:4160
	ds_read_b128 v[68:71], v229 offset:62464
	v_add_f32_e32 v45, 1.0, v65
	v_rcp_f32_e32 v66, v45
	s_nop 0
	v_mul_f32_e32 v65, v65, v66
	v_cndmask_b32_e32 v115, 1.0, v65, vcc
	v_or_b32_e32 v65, 26, v75
	v_cndmask_b32_e32 v45, 0, v66, vcc
	v_cmp_lt_i32_e32 vcc, v65, v72
	v_exp_f32_e32 v65, v46
	v_mul_f32_e32 v64, v64, v115
	v_add_f32_e32 v46, 1.0, v65
	v_rcp_f32_e32 v66, v46
	s_nop 0
	v_mul_f32_e32 v65, v65, v66
	v_cndmask_b32_e32 v148, 1.0, v65, vcc
	v_or_b32_e32 v65, 27, v75
	v_cndmask_b32_e32 v46, 0, v66, vcc
	v_cmp_lt_i32_e32 vcc, v65, v72
	v_exp_f32_e32 v65, v47
	s_nop 0
	v_add_f32_e32 v47, 1.0, v65
	v_rcp_f32_e32 v66, v47
	s_nop 0
	v_mul_f32_e32 v65, v65, v66
	v_cndmask_b32_e32 v149, 1.0, v65, vcc
	v_mul_f32_e32 v65, v148, v149
	v_cndmask_b32_e32 v47, 0, v66, vcc
	v_mul_f32_e32 v64, v64, v65
	v_min_f32_e64 v48, -v48, s98
	v_exp_f32_e32 v48, v48
	v_min_f32_e64 v49, -v49, s98
	v_exp_f32_e32 v49, v49
	v_add_f32_e32 v66, 1.0, v48
	v_or_b32_e32 v65, 32, v75
	v_rcp_f32_e32 v66, v66
	v_cmp_lt_i32_e32 vcc, v65, v72
	v_add_f32_e32 v65, 1.0, v49
	v_min_f32_e64 v50, -v50, s98
	v_rcp_f32_e32 v65, v65
	v_exp_f32_e32 v50, v50
	v_cndmask_b32_e32 v80, 0, v66, vcc
	v_mul_f32_e32 v48, v48, v66
	v_or_b32_e32 v66, 33, v75
	v_cndmask_b32_e32 v48, 1.0, v48, vcc
	v_cmp_lt_i32_e32 vcc, v66, v72
	v_max_f32_e64 v51, -v51, -v51
	v_mul_f32_e32 v49, v49, v65
	v_cndmask_b32_e32 v81, 0, v65, vcc
	v_add_f32_e32 v65, 1.0, v50
	v_min_f32_e32 v51, 0x42700000, v51
	v_rcp_f32_e32 v65, v65
	v_exp_f32_e32 v51, v51
	v_cndmask_b32_e32 v150, 1.0, v49, vcc
	v_or_b32_e32 v49, 34, v75
	s_waitcnt lgkmcnt(0)
	v_mfma_f32_32x32x16_bf16 v[0:15], v[82:85], v[68:71], v[0:15]
	v_cmp_lt_i32_e32 vcc, v49, v72
	v_mul_f32_e32 v49, v50, v65
	v_add_f32_e32 v50, 1.0, v51
	v_rcp_f32_e32 v50, v50
	ds_read_b128 v[86:89], v77 offset:4672
	v_cndmask_b32_e32 v151, 1.0, v49, vcc
	v_or_b32_e32 v49, 35, v75
	v_cndmask_b32_e32 v82, 0, v65, vcc
	v_cmp_lt_i32_e32 vcc, v49, v72
	v_mul_f32_e32 v49, v51, v50
	v_mul_f32_e32 v104, v48, v150
	v_cndmask_b32_e32 v152, 1.0, v49, vcc
	v_cndmask_b32_e32 v83, 0, v50, vcc
	v_mul_f32_e32 v78, v151, v152
	v_min_f32_e64 v52, -v52, s98
	v_exp_f32_e32 v52, v52
	v_or_b32_e32 v65, 40, v75
	v_cmp_lt_i32_e32 vcc, v65, v72
	s_waitcnt lgkmcnt(0)
	v_mfma_f32_32x32x16_bf16 v[16:31], v[86:89], v[68:71], v[16:31]
	v_add_f32_e32 v65, 1.0, v52
	v_rcp_f32_e32 v65, v65
	ds_read_b128 v[90:93], v77 offset:6240
	ds_read_b128 v[48:51], v229 offset:63488
	v_mul_f32_e32 v52, v52, v65
	v_cndmask_b32_e32 v68, 1.0, v52, vcc
	v_or_b32_e32 v52, 41, v75
	v_cndmask_b32_e32 v84, 0, v65, vcc
	v_cmp_lt_i32_e32 vcc, v52, v72
	v_max_f32_e64 v52, -v53, -v53
	v_min_f32_e32 v52, 0x42700000, v52
	v_exp_f32_e32 v52, v52
	s_nop 0
	v_add_f32_e32 v53, 1.0, v52
	v_rcp_f32_e32 v53, v53
	s_nop 0
	v_mul_f32_e32 v52, v52, v53
	v_cndmask_b32_e32 v66, 1.0, v52, vcc
	v_or_b32_e32 v52, 42, v75
	v_cndmask_b32_e32 v85, 0, v53, vcc
	v_cmp_lt_i32_e32 vcc, v52, v72
	v_max_f32_e64 v52, -v54, -v54
	v_min_f32_e32 v52, 0x42700000, v52
	v_exp_f32_e32 v52, v52
	s_nop 0
	v_add_f32_e32 v53, 1.0, v52
	v_rcp_f32_e32 v53, v53
	s_nop 0
	v_cndmask_b32_e32 v86, 0, v53, vcc
	v_mul_f32_e32 v52, v52, v53
	v_or_b32_e32 v53, 43, v75
	v_cndmask_b32_e32 v52, 1.0, v52, vcc
	v_cmp_lt_i32_e32 vcc, v53, v72
	v_max_f32_e64 v53, -v55, -v55
	v_min_f32_e32 v53, 0x42700000, v53
	v_exp_f32_e32 v53, v53
	s_nop 0
	v_add_f32_e32 v54, 1.0, v53
	v_rcp_f32_e32 v54, v54
	s_nop 0
	v_mul_f32_e32 v53, v53, v54
	v_cndmask_b32_e32 v87, 0, v54, vcc
	v_cndmask_b32_e32 v54, 1.0, v53, vcc
	v_min_f32_e64 v53, -v56, s98
	v_exp_f32_e32 v53, v53
	v_min_f32_e64 v57, -v57, s98
	v_or_b32_e32 v55, 48, v75
	v_add_f32_e32 v56, 1.0, v53
	v_rcp_f32_e32 v56, v56
	v_exp_f32_e32 v57, v57
	v_cmp_lt_i32_e32 vcc, v55, v72
	s_waitcnt lgkmcnt(0)
	v_mfma_f32_32x32x16_bf16 v[0:15], v[90:93], v[48:51], v[0:15]
	v_mul_f32_e32 v53, v53, v56
	v_cndmask_b32_e32 v88, 0, v56, vcc
	v_or_b32_e32 v56, 49, v75
	v_cndmask_b32_e32 v53, 1.0, v53, vcc
	v_cmp_lt_i32_e32 vcc, v56, v72
	v_max_f32_e64 v56, -v58, -v58
	v_add_f32_e32 v55, 1.0, v57
	v_min_f32_e32 v56, 0x42700000, v56
	v_rcp_f32_e32 v55, v55
	v_exp_f32_e32 v56, v56
	v_max_f32_e64 v58, -v59, -v59
	v_min_f32_e32 v58, 0x42700000, v58
	v_cndmask_b32_e32 v89, 0, v55, vcc
	v_mul_f32_e32 v55, v57, v55
	v_add_f32_e32 v57, 1.0, v56
	v_rcp_f32_e32 v57, v57
	v_exp_f32_e32 v58, v58
	v_cndmask_b32_e32 v153, 1.0, v55, vcc
	v_or_b32_e32 v55, 50, v75
	v_cmp_lt_i32_e32 vcc, v55, v72
	v_mul_f32_e32 v55, v56, v57
	v_add_f32_e32 v56, 1.0, v58
	v_rcp_f32_e32 v56, v56
	v_cndmask_b32_e32 v158, 1.0, v55, vcc
	v_or_b32_e32 v55, 51, v75
	ds_read_b128 v[154:157], v77 offset:6752
	v_cndmask_b32_e32 v90, 0, v57, vcc
	v_cmp_lt_i32_e32 vcc, v55, v72
	v_mul_f32_e32 v55, v58, v56
	v_mul_f32_e32 v53, v53, v153
	v_cndmask_b32_e32 v159, 1.0, v55, vcc
	v_mul_f32_e32 v55, v158, v159
	v_cndmask_b32_e32 v91, 0, v56, vcc
	v_mul_f32_e32 v69, v53, v55
	s_waitcnt lgkmcnt(0)
	v_mfma_f32_32x32x16_bf16 v[16:31], v[154:157], v[48:51], v[16:31]
	v_or_b32_e32 v48, 56, v75
	v_cmp_lt_i32_e32 vcc, v48, v72
	v_max_f32_e64 v48, -v60, -v60
	v_min_f32_e32 v48, 0x42700000, v48
	v_exp_f32_e32 v48, v48
	s_nop 0
	v_add_f32_e32 v49, 1.0, v48
	v_rcp_f32_e32 v49, v49
	s_nop 0
	v_cndmask_b32_e32 v92, 0, v49, vcc
	v_mul_f32_e32 v48, v48, v49
	v_or_b32_e32 v49, 57, v75
	v_cndmask_b32_e32 v48, 1.0, v48, vcc
	v_cmp_lt_i32_e32 vcc, v49, v72
	v_max_f32_e64 v49, -v61, -v61
	v_min_f32_e32 v49, 0x42700000, v49
	v_exp_f32_e32 v49, v49
	s_nop 0
	v_add_f32_e32 v50, 1.0, v49
	v_rcp_f32_e32 v50, v50
	s_nop 0
	v_mul_f32_e32 v49, v49, v50
	v_cndmask_b32_e32 v156, 1.0, v49, vcc
	v_or_b32_e32 v49, 58, v75
	v_cndmask_b32_e32 v93, 0, v50, vcc
	v_cmp_lt_i32_e32 vcc, v49, v72
	v_max_f32_e64 v49, -v62, -v62
	v_min_f32_e32 v49, 0x42700000, v49
	v_exp_f32_e32 v49, v49
	v_mul_f32_e32 v48, v48, v156
	v_add_f32_e32 v50, 1.0, v49
	v_rcp_f32_e32 v50, v50
	s_nop 0
	v_mul_f32_e32 v49, v49, v50
	v_cndmask_b32_e32 v157, 1.0, v49, vcc
	v_or_b32_e32 v49, 59, v75
	v_cndmask_b32_e32 v94, 0, v50, vcc
	v_cmp_lt_i32_e32 vcc, v49, v72
	v_max_f32_e64 v49, -v63, -v63
	v_min_f32_e32 v49, 0x42700000, v49
	v_exp_f32_e32 v49, v49
	s_nop 0
	v_add_f32_e32 v50, 1.0, v49
	v_rcp_f32_e32 v50, v50
	s_nop 0
	v_mul_f32_e32 v49, v49, v50
	v_cndmask_b32_e32 v164, 1.0, v49, vcc
	v_mul_f32_e32 v49, v157, v164
	v_cndmask_b32_e32 v95, 0, v50, vcc
	v_mul_f32_e32 v53, v48, v49
	v_mov_b32_e32 v48, v106
	v_mov_b32_e32 v49, v106
	s_nop 1
	v_permlane32_swap_b32_e32 v48, v49
	v_cndmask_b32_e64 v165, v48, v49, s[34:35]
	v_mov_b32_e32 v48, v74
	v_mov_b32_e32 v49, v74
	s_nop 1
	v_permlane32_swap_b32_e32 v48, v49
	v_cndmask_b32_e64 v48, v48, v49, s[34:35]
	v_mov_b32_e32 v49, v76
	v_mov_b32_e32 v50, v76
	s_nop 1
	v_permlane32_swap_b32_e32 v49, v50
	v_cndmask_b32_e64 v50, v49, v50, s[34:35]
	v_mov_b32_e32 v49, v64
	v_mov_b32_e32 v51, v64
	s_nop 1
	v_permlane32_swap_b32_e32 v49, v51
	v_cndmask_b32_e64 v56, v49, v51, s[34:35]
	v_mov_b32_e32 v49, v69
	v_mov_b32_e32 v51, v69
	s_nop 1
	v_permlane32_swap_b32_e32 v49, v51
	v_cndmask_b32_e64 v67, v49, v51, s[34:35]
	v_mov_b32_e32 v49, v53
	v_mov_b32_e32 v51, v53
	s_nop 1
	v_permlane32_swap_b32_e32 v49, v51
	v_cndmask_b32_e64 v55, v49, v51, s[34:35]
	v_pk_mul_f32 v[154:155], v[52:53], v[54:55]
	v_pk_mul_f32 v[58:59], v[68:69], v[66:67]
	v_cndmask_b32_e64 v166, 1.0, v55, s[34:35]
	v_pk_mul_f32 v[58:59], v[58:59], v[154:155]
	s_nop 0
	v_mov_b32_e32 v49, v58
	v_mov_b32_e32 v51, v58
	s_nop 1
	v_permlane32_swap_b32_e32 v49, v51
	v_cndmask_b32_e64 v79, v49, v51, s[34:35]
	v_mov_b32_e32 v105, v58
	v_pk_mul_f32 v[60:61], v[104:105], v[78:79]
	v_cndmask_b32_e64 v105, 1.0, v67, s[34:35]
	v_mov_b32_e32 v49, v60
	v_mov_b32_e32 v51, v60
	s_nop 1
	v_permlane32_swap_b32_e32 v49, v51
	v_cndmask_b32_e64 v58, v49, v51, s[34:35]
	v_pk_mul_f32 v[60:61], v[60:61], v[58:59]
	v_cndmask_b32_e64 v53, 1.0, v58, s[34:35]
	v_mov_b32_e32 v65, v60
	v_mov_b32_e32 v57, v61
	v_pk_mul_f32 v[62:63], v[64:65], v[56:57]
	v_mul_f32_e32 v105, v105, v155
	v_mov_b32_e32 v77, v62
	v_mov_b32_e32 v51, v63
	v_pk_mul_f32 v[64:65], v[76:77], v[50:51]
	v_cndmask_b32_e64 v50, 1.0, v50, s[34:35]
	v_mov_b32_e32 v75, v64
	v_mov_b32_e32 v49, v65
	v_pk_mul_f32 v[70:71], v[74:75], v[48:49]
	v_cndmask_b32_e64 v49, 1.0, v165, s[34:35]
	v_mul_f32_e32 v104, v70, v71
	v_mul_f32_e32 v49, v49, v104
	v_cndmask_b32_e64 v48, 1.0, v48, s[34:35]
	v_mul_f32_e32 v55, v108, v49
	v_mul_f32_e32 v57, v107, v55
	v_mul_f32_e32 v55, v34, v55
	v_mul_f32_e32 v49, v35, v49
	v_mul_f32_e32 v48, v48, v71
	v_cvt_pk_bf16_f32 v69, v55, v49
	v_mul_f32_e32 v49, v111, v48
	v_mul_f32_e32 v58, v73, v57
	v_mul_f32_e32 v55, v110, v49
	v_mul_f32_e32 v49, v38, v49
	v_mul_f32_e32 v48, v39, v48
	v_mul_f32_e32 v58, v32, v58
	v_mul_f32_e32 v57, v33, v57
	v_cvt_pk_bf16_f32 v71, v49, v48
	v_mul_f32_e32 v48, v50, v65
	v_cvt_pk_bf16_f32 v68, v58, v57
	v_mul_f32_e32 v57, v109, v55
	v_mul_f32_e32 v49, v114, v48
	v_cndmask_b32_e64 v51, 1.0, v56, s[34:35]
	v_mul_f32_e32 v57, v36, v57
	v_mul_f32_e32 v55, v37, v55
	v_mul_f32_e32 v50, v113, v49
	v_mul_f32_e32 v49, v42, v49
	v_mul_f32_e32 v48, v43, v48
	v_cvt_pk_bf16_f32 v70, v57, v55
	v_mul_f32_e32 v55, v112, v50
	v_cvt_pk_bf16_f32 v109, v49, v48
	v_mul_f32_e32 v48, v51, v63
	v_mul_f32_e32 v55, v40, v55
	v_mul_f32_e32 v50, v41, v50
	v_mul_f32_e32 v49, v149, v48
	v_cvt_pk_bf16_f32 v108, v55, v50
	v_mul_f32_e32 v50, v148, v49
	v_mul_f32_e32 v49, v46, v49
	v_mul_f32_e32 v48, v47, v48
	v_mul_f32_e32 v51, v115, v50
	v_cvt_pk_bf16_f32 v111, v49, v48
	v_mul_f32_e32 v48, v53, v61
	v_mul_f32_e32 v51, v44, v51
	v_mul_f32_e32 v50, v45, v50
	v_mul_f32_e32 v49, v152, v48
	v_cvt_pk_bf16_f32 v110, v51, v50
	v_mul_f32_e32 v50, v151, v49
	v_mul_f32_e32 v51, v150, v50
	v_mul_f32_e32 v51, v80, v51
	v_mul_f32_e32 v50, v81, v50
	v_add_u32_e32 v107, s17, v201
	v_cvt_pk_bf16_f32 v112, v51, v50
	v_mul_f32_e32 v53, v82, v49
	v_mul_f32_e32 v55, v83, v48
	ds_read_b64_tr_b16 v[48:49], v107 offset:16640
	ds_read_b64_tr_b16 v[50:51], v107 offset:17152
	v_cndmask_b32_e64 v56, 1.0, v79, s[34:35]
	v_mul_f32_e32 v115, v56, v59
	v_mul_f32_e32 v72, v54, v115
	v_mul_f32_e32 v73, v52, v72
	v_cvt_pk_bf16_f32 v113, v53, v55
	s_waitcnt lgkmcnt(0)
	v_mfma_f32_32x32x16_bf16 v[48:63], v[68:71], v[48:51], 0
	v_mul_f32_e32 v74, v66, v73
	ds_read_b64_tr_b16 v[64:65], v107 offset:20800
	ds_read_b64_tr_b16 v[66:67], v107 offset:21312
	ds_read_b64_tr_b16 v[148:149], v107 offset:17664
	ds_read_b64_tr_b16 v[150:151], v107 offset:18176
	v_mul_f32_e32 v74, v84, v74
	v_mul_f32_e32 v73, v85, v73
	v_cvt_pk_bf16_f32 v114, v74, v73
	v_mul_f32_e32 v152, v86, v72
	s_waitcnt lgkmcnt(2)
	v_mfma_f32_32x32x16_bf16 v[64:79], v[68:71], v[64:67], 0
	v_mul_f32_e32 v115, v87, v115
	v_cvt_pk_bf16_f32 v115, v152, v115
	v_mul_f32_e32 v154, v159, v105
	v_mul_f32_e32 v152, v158, v154
	v_mul_f32_e32 v153, v153, v152
	v_mul_f32_e32 v153, v88, v153
	v_mul_f32_e32 v152, v89, v152
	s_waitcnt lgkmcnt(0)
	v_mfma_f32_32x32x16_bf16 v[48:63], v[108:111], v[148:151], v[48:63]
	ds_read_b64_tr_b16 v[148:149], v107 offset:21824
	ds_read_b64_tr_b16 v[150:151], v107 offset:22336
	v_cvt_pk_bf16_f32 v152, v153, v152
	v_mul_f32_e32 v153, v90, v154
	v_mul_f32_e32 v105, v91, v105
	v_cvt_pk_bf16_f32 v153, v153, v105
	v_mul_f32_e32 v105, v164, v166
	s_waitcnt lgkmcnt(0)
	v_mfma_f32_32x32x16_bf16 v[64:79], v[108:111], v[148:151], v[64:79]
	ds_read_b64_tr_b16 v[108:109], v107 offset:18688
	ds_read_b64_tr_b16 v[110:111], v107 offset:19200
	v_mul_f32_e32 v148, v157, v105
	v_mul_f32_e32 v149, v156, v148
	v_mul_f32_e32 v149, v92, v149
	v_mul_f32_e32 v148, v93, v148
	v_cvt_pk_bf16_f32 v154, v149, v148
	v_mul_f32_e32 v105, v94, v105
	s_waitcnt lgkmcnt(0)
	v_mfma_f32_32x32x16_bf16 v[48:63], v[112:115], v[108:111], v[48:63]
	ds_read_b64_tr_b16 v[108:109], v107 offset:22848
	ds_read_b64_tr_b16 v[110:111], v107 offset:23360
	v_mul_f32_e32 v148, v95, v166
	v_cvt_pk_bf16_f32 v155, v105, v148
	v_mul_f32_e32 v105, v106, v165
	s_waitcnt lgkmcnt(0)
	v_mfma_f32_32x32x16_bf16 v[64:79], v[112:115], v[108:111], v[64:79]
	ds_read_b64_tr_b16 v[108:109], v107 offset:19712
	ds_read_b64_tr_b16 v[110:111], v107 offset:20224
	s_waitcnt lgkmcnt(0)
	v_mfma_f32_32x32x16_bf16 v[48:63], v[152:155], v[108:111], v[48:63]
	ds_read_b64_tr_b16 v[108:109], v107 offset:23872
	ds_read_b64_tr_b16 v[110:111], v107 offset:24384
	v_mul_f32_e32 v107, v105, v104
	s_waitcnt lgkmcnt(0)
	v_mfma_f32_32x32x16_bf16 v[64:79], v[152:155], v[108:111], v[64:79]
	s_and_saveexec_b64 s[4:5], s[36:37]
	s_cbranch_execnz .LBB0_470
	s_or_b64 exec, exec, s[4:5]
	s_andn2_b64 vcc, exec, s[12:13]
	s_cbranch_vccz .LBB0_471

.LBB0_436:
	v_cmp_neq_f32_e32 vcc, 0, v107
	s_cbranch_vccz .LBB0_438
	ds_read_b128 v[32:35], v236
	ds_read_b128 v[80:83], v229 offset:60416
	v_min_f32_e64 v0, -v0, s98
	v_min_f32_e64 v1, -v1, s98
	v_min_f32_e64 v2, -v2, s98
	v_min_f32_e64 v3, -v3, s98
	v_exp_f32_e32 v108, v0
	v_exp_f32_e32 v88, v1
	v_exp_f32_e32 v110, v2
	v_exp_f32_e32 v112, v3
	s_waitcnt lgkmcnt(0)
	v_mfma_f32_32x32x16_bf16 v[32:47], v[32:35], v[80:83], 0
	ds_read_b128 v[84:87], v236 offset:512
	v_add_f32_e32 v0, 1.0, v108
	v_add_f32_e32 v1, 1.0, v88
	v_add_f32_e32 v2, 1.0, v110
	v_add_f32_e32 v3, 1.0, v112
	v_rcp_f32_e32 v0, v0
	v_rcp_f32_e32 v1, v1
	v_rcp_f32_e32 v2, v2
	v_rcp_f32_e32 v3, v3
	v_mul_f32_e32 v104, v88, v1
	v_min_f32_e64 v4, -v4, s98
	v_min_f32_e64 v5, -v5, s98
	v_min_f32_e64 v6, -v6, s98
	v_min_f32_e64 v7, -v7, s98
	v_exp_f32_e32 v114, v4
	v_exp_f32_e32 v115, v5
	v_exp_f32_e32 v148, v6
	v_exp_f32_e32 v149, v7
	s_waitcnt lgkmcnt(0)
	v_mfma_f32_32x32x16_bf16 v[80:95], v[84:87], v[80:83], 0
	v_add_f32_e32 v4, 1.0, v114
	v_add_f32_e32 v5, 1.0, v115
	v_add_f32_e32 v6, 1.0, v148
	v_add_f32_e32 v7, 1.0, v149
	ds_read_b128 v[164:167], v236 offset:2080
	ds_read_b128 v[168:171], v229 offset:61440
	v_rcp_f32_e32 v4, v4
	v_rcp_f32_e32 v5, v5
	v_rcp_f32_e32 v6, v6
	v_rcp_f32_e32 v7, v7
	v_pk_mul_f32 v[114:115], v[114:115], v[4:5]
	s_nop 0
	v_pk_mul_f32 v[156:157], v[114:115], v[114:115] op_sel_hi:[0,1]
	v_pk_mul_f32 v[150:151], v[148:149], v[6:7]
	s_nop 0
	v_pk_mul_f32 v[154:155], v[150:151], v[150:151] op_sel_hi:[0,1]
	v_min_f32_e64 v9, -v9, s98
	s_waitcnt lgkmcnt(0)
	v_mfma_f32_32x32x16_bf16 v[32:47], v[164:167], v[168:171], v[32:47]
	v_exp_f32_e32 v164, v9
	v_min_f32_e64 v8, -v8, s98
	v_exp_f32_e32 v8, v8
	v_add_f32_e32 v9, 1.0, v164
	v_rcp_f32_e32 v152, v9
	v_min_f32_e64 v9, -v10, s98
	v_exp_f32_e32 v9, v9
	v_add_f32_e32 v105, 1.0, v8
	v_rcp_f32_e32 v148, v105
	ds_read_b128 v[172:175], v236 offset:2592
	v_add_f32_e32 v10, 1.0, v9
	v_rcp_f32_e32 v149, v10
	v_min_f32_e64 v10, -v11, s98
	v_exp_f32_e32 v165, v10
	v_pk_mul_f32 v[158:159], v[8:9], v[148:149]
	v_add_f32_e32 v10, 1.0, v165
	v_rcp_f32_e32 v153, v10
	s_nop 0
	v_pk_mul_f32 v[164:165], v[164:165], v[152:153]
	s_nop 0
	v_pk_mul_f32 v[8:9], v[158:159], v[164:165]
	s_nop 0
	v_pk_mul_f32 v[166:167], v[8:9], v[8:9] op_sel:[0,1] op_sel_hi:[1,0]
	v_min_f32_e64 v8, -v12, s98
	s_waitcnt lgkmcnt(0)
	v_mfma_f32_32x32x16_bf16 v[80:95], v[172:175], v[168:171], v[80:95]
	v_exp_f32_e32 v168, v8
	ds_read_b128 v[176:179], v236 offset:4160
	ds_read_b128 v[182:185], v229 offset:62464
	v_mov_b32_e32 v9, v152
	v_mov_b32_e32 v10, v149
	v_add_f32_e32 v8, 1.0, v168
	v_rcp_f32_e32 v12, v8
	v_min_f32_e64 v8, -v13, s98
	v_exp_f32_e32 v170, v8
	v_mov_b32_e32 v172, v12
	v_mov_b32_e32 v11, v153
	v_add_f32_e32 v8, 1.0, v170
	v_rcp_f32_e32 v13, v8
	v_min_f32_e64 v8, -v14, s98
	v_exp_f32_e32 v169, v8
	s_nop 0
	v_add_f32_e32 v8, 1.0, v169
	v_rcp_f32_e32 v14, v8
	v_min_f32_e64 v8, -v15, s98
	v_exp_f32_e32 v171, v8
	v_mov_b32_e32 v173, v14
	v_pk_mul_f32 v[168:169], v[168:169], v[172:173]
	v_mov_b32_e32 v172, v13
	v_add_f32_e32 v8, 1.0, v171
	v_rcp_f32_e32 v15, v8
	v_mov_b32_e32 v8, v148
	v_mov_b32_e32 v173, v15
	v_pk_mul_f32 v[170:171], v[170:171], v[172:173]
	s_nop 0
	v_pk_mul_f32 v[172:173], v[168:169], v[170:171]
	s_nop 0
	v_mul_f32_e32 v105, v172, v173
	v_min_f32_e64 v17, -v17, s98
	v_exp_f32_e32 v106, v17
	v_min_f32_e64 v18, -v18, s98
	v_add_f32_e32 v17, 1.0, v106
	v_rcp_f32_e32 v17, v17
	v_min_f32_e64 v16, -v16, s98
	v_min_f32_e64 v19, -v19, s98
	s_waitcnt lgkmcnt(0)
	v_mfma_f32_32x32x16_bf16 v[32:47], v[176:179], v[182:185], v[32:47]
	v_exp_f32_e32 v176, v16
	v_mul_f32_e32 v172, v106, v17
	v_exp_f32_e32 v180, v18
	v_exp_f32_e32 v106, v19
	v_add_f32_e32 v16, 1.0, v176
	ds_read_b128 v[186:189], v236 offset:4672
	v_add_f32_e32 v18, 1.0, v180
	v_add_f32_e32 v19, 1.0, v106
	v_rcp_f32_e32 v16, v16
	v_rcp_f32_e32 v18, v18
	v_rcp_f32_e32 v19, v19
	v_min_f32_e64 v20, -v20, s98
	v_min_f32_e64 v21, -v21, s98
	v_min_f32_e64 v22, -v22, s98
	v_min_f32_e64 v23, -v23, s98
	v_exp_f32_e32 v174, v20
	v_exp_f32_e32 v175, v21
	v_exp_f32_e32 v178, v22
	v_exp_f32_e32 v179, v23
	s_waitcnt lgkmcnt(0)
	v_mfma_f32_32x32x16_bf16 v[80:95], v[186:189], v[182:185], v[80:95]
	v_add_f32_e32 v20, 1.0, v174
	v_add_f32_e32 v21, 1.0, v175
	v_add_f32_e32 v22, 1.0, v178
	v_add_f32_e32 v23, 1.0, v179
	ds_read_b128 v[238:241], v236 offset:6240
	ds_read_b128 v[242:245], v229 offset:63488
	v_rcp_f32_e32 v20, v20
	v_rcp_f32_e32 v21, v21
	v_rcp_f32_e32 v22, v22
	v_rcp_f32_e32 v23, v23
	v_pk_mul_f32 v[174:175], v[174:175], v[20:21]
	s_nop 0
	v_pk_mul_f32 v[250:251], v[174:175], v[174:175] op_sel_hi:[0,1]
	v_pk_mul_f32 v[178:179], v[178:179], v[22:23]
	s_nop 0
	v_pk_mul_f32 v[252:253], v[178:179], v[178:179] op_sel_hi:[0,1]
	v_min_f32_e64 v25, -v25, s98
	v_exp_f32_e32 v188, v25
	v_min_f32_e64 v24, -v24, s98
	v_exp_f32_e32 v24, v24
	v_add_f32_e32 v25, 1.0, v188
	v_rcp_f32_e32 v184, v25
	v_min_f32_e64 v25, -v26, s98
	v_exp_f32_e32 v25, v25
	s_waitcnt lgkmcnt(0)
	v_mfma_f32_32x32x16_bf16 v[32:47], v[238:241], v[242:245], v[32:47]
	v_add_f32_e32 v109, 1.0, v24
	v_rcp_f32_e32 v182, v109
	v_add_f32_e32 v26, 1.0, v25
	v_rcp_f32_e32 v183, v26
	v_min_f32_e64 v26, -v27, s98
	v_exp_f32_e32 v189, v26
	ds_read_b128 v[246:249], v236 offset:6752
	v_pk_mul_f32 v[186:187], v[24:25], v[182:183]
	v_add_f32_e32 v26, 1.0, v189
	v_rcp_f32_e32 v185, v26
	s_nop 0
	v_pk_mul_f32 v[188:189], v[188:189], v[184:185]
	s_nop 0
	v_pk_mul_f32 v[24:25], v[186:187], v[188:189]
	s_nop 0
	v_pk_mul_f32 v[238:239], v[24:25], v[24:25] op_sel:[0,1] op_sel_hi:[1,0]
	v_min_f32_e64 v24, -v28, s98
	v_exp_f32_e32 v240, v24
	s_waitcnt lgkmcnt(0)
	v_mfma_f32_32x32x16_bf16 v[80:95], v[246:249], v[242:245], v[80:95]
	v_mov_b32_e32 v25, v184
	v_mov_b32_e32 v26, v183
	v_add_f32_e32 v24, 1.0, v240
	v_rcp_f32_e32 v28, v24
	v_min_f32_e64 v24, -v29, s98
	v_exp_f32_e32 v242, v24
	v_mov_b32_e32 v244, v28
	v_mov_b32_e32 v27, v185
	v_add_f32_e32 v24, 1.0, v242
	v_rcp_f32_e32 v29, v24
	v_min_f32_e64 v24, -v30, s98
	v_exp_f32_e32 v241, v24
	s_nop 0
	v_add_f32_e32 v24, 1.0, v241
	v_rcp_f32_e32 v30, v24
	v_min_f32_e64 v24, -v31, s98
	v_exp_f32_e32 v243, v24
	v_mov_b32_e32 v245, v30
	v_pk_mul_f32 v[244:245], v[240:241], v[244:245]
	v_mov_b32_e32 v240, v29
	v_add_f32_e32 v24, 1.0, v243
	v_rcp_f32_e32 v31, v24
	v_mov_b32_e32 v24, v182
	v_mov_b32_e32 v241, v31
	v_pk_mul_f32 v[242:243], v[242:243], v[240:241]
	s_nop 0
	v_pk_mul_f32 v[240:241], v[244:245], v[242:243]
	s_nop 0
	v_mul_f32_e32 v109, v240, v241
	v_mov_b32_e32 v111, v166
	v_mov_b32_e32 v113, v166
	s_nop 1
	v_permlane32_swap_b32_e32 v111, v113
	v_cndmask_b32_e64 v167, v111, v113, s[34:35]
	v_mov_b32_e32 v111, v105
	v_mov_b32_e32 v113, v105
	s_nop 1
	v_permlane32_swap_b32_e32 v111, v113
	v_cndmask_b32_e64 v114, v111, v113, s[34:35]
	v_mov_b32_e32 v111, v238
	v_mov_b32_e32 v113, v238
	s_nop 1
	v_permlane32_swap_b32_e32 v111, v113
	v_cndmask_b32_e64 v239, v111, v113, s[34:35]
	v_mov_b32_e32 v111, v109
	v_mov_b32_e32 v113, v109
	s_nop 1
	v_permlane32_swap_b32_e32 v111, v113
	v_mov_b32_e32 v177, v251
	v_mov_b32_e32 v252, v16
	v_cndmask_b32_e64 v156, v111, v113, s[34:35]
	v_pk_mul_f32 v[176:177], v[176:177], v[252:253]
	v_mul_f32_e32 v241, v109, v156
	v_mov_b32_e32 v109, v177
	v_mov_b32_e32 v111, v177
	s_nop 1
	v_permlane32_swap_b32_e32 v109, v111
	v_mov_b32_e32 v240, v19
	v_mov_b32_e32 v181, v238
	v_mov_b32_e32 v238, v18
	v_cndmask_b32_e64 v173, v109, v111, s[34:35]
	v_pk_mul_f32 v[246:247], v[106:107], v[240:241]
	v_pk_mul_f32 v[180:181], v[180:181], v[238:239]
	v_pk_mul_f32 v[176:177], v[176:177], v[172:173]
	v_pk_mul_f32 v[248:249], v[180:181], v[246:247]
	v_mov_b32_e32 v154, v0
	v_pk_mul_f32 v[176:177], v[176:177], v[248:249]
	v_mul_f32_e32 v113, v105, v114
	v_mov_b32_e32 v106, v176
	v_mov_b32_e32 v109, v176
	s_nop 1
	v_permlane32_swap_b32_e32 v106, v109
	v_cndmask_b32_e64 v106, v106, v109, s[34:35]
	v_mul_f32_e32 v109, v176, v106
	v_mul_f32_e32 v251, v109, v177
	v_mov_b32_e32 v109, v157
	v_pk_mul_f32 v[108:109], v[108:109], v[154:155]
	v_mov_b32_e32 v250, v3
	v_mov_b32_e32 v105, v109
	v_mov_b32_e32 v111, v109
	s_nop 1
	v_permlane32_swap_b32_e32 v105, v111
	v_cndmask_b32_e64 v105, v105, v111, s[34:35]
	v_mov_b32_e32 v111, v166
	v_mov_b32_e32 v166, v2
	v_pk_mul_f32 v[112:113], v[112:113], v[250:251]
	v_pk_mul_f32 v[110:111], v[110:111], v[166:167]
	v_pk_mul_f32 v[108:109], v[108:109], v[104:105]
	v_pk_mul_f32 v[154:155], v[110:111], v[112:113]
	v_cndmask_b32_e64 v166, 1.0, v239, s[34:35]
	v_pk_mul_f32 v[108:109], v[108:109], v[154:155]
	v_cndmask_b32_e64 v157, 1.0, v167, s[34:35]
	v_mov_b32_e32 v111, v108
	v_mov_b32_e32 v154, v108
	s_nop 1
	v_permlane32_swap_b32_e32 v111, v154
	v_cndmask_b32_e64 v111, v111, v154, s[34:35]
	v_mul_f32_e32 v108, v108, v111
	v_mul_f32_e32 v154, v108, v109
	v_cndmask_b32_e64 v108, 1.0, v111, s[34:35]
	v_mul_f32_e32 v109, v108, v109
	v_mul_f32_e32 v108, v112, v109
	v_cndmask_b32_e64 v111, 1.0, v105, s[34:35]
	v_mul_f32_e32 v105, v110, v108
	v_mul_f32_e32 v104, v104, v105
	v_pk_mul_f32 v[104:105], v[0:1], v[104:105]
	v_mov_b32_e32 v110, v148
	v_cvt_pk_bf16_f32 v238, v104, v105
	v_pk_mul_f32 v[104:105], v[2:3], v[108:109]
	v_cndmask_b32_e64 v114, 1.0, v114, s[34:35]
	v_cvt_pk_bf16_f32 v239, v104, v105
	v_mul_f32_e32 v105, v111, v155
	v_mul_f32_e32 v104, v151, v105
	v_mul_f32_e32 v109, v150, v104
	v_pk_mul_f32 v[104:105], v[6:7], v[104:105]
	v_mul_f32_e32 v108, v115, v109
	v_cvt_pk_bf16_f32 v241, v104, v105
	v_mul_f32_e32 v105, v157, v113
	v_pk_mul_f32 v[108:109], v[4:5], v[108:109]
	v_mul_f32_e32 v104, v165, v105
	v_cvt_pk_bf16_f32 v240, v108, v109
	v_mul_f32_e32 v109, v159, v104
	v_mul_f32_e32 v108, v164, v109
	v_mov_b32_e32 v111, v152
	v_mov_b32_e32 v152, v149
	v_pk_mul_f32 v[108:109], v[110:111], v[108:109]
	v_pk_mul_f32 v[104:105], v[152:153], v[104:105]
	v_cvt_pk_bf16_f32 v108, v108, v109
	v_cvt_pk_bf16_f32 v109, v104, v105
	v_mul_f32_e32 v105, v114, v251
	v_mul_f32_e32 v104, v171, v105
	v_mul_f32_e32 v111, v169, v104
	v_mul_f32_e32 v110, v170, v111
	v_cndmask_b32_e64 v106, 1.0, v106, s[34:35]
	v_pk_mul_f32 v[110:111], v[12:13], v[110:111]
	v_pk_mul_f32 v[104:105], v[14:15], v[104:105]
	v_cvt_pk_bf16_f32 v110, v110, v111
	v_cvt_pk_bf16_f32 v111, v104, v105
	v_mul_f32_e32 v105, v106, v177
	v_mul_f32_e32 v104, v246, v105
	v_mul_f32_e32 v113, v180, v104
	v_mul_f32_e32 v112, v172, v113
	v_cndmask_b32_e64 v158, 1.0, v173, s[34:35]
	v_pk_mul_f32 v[112:113], v[16:17], v[112:113]
	v_pk_mul_f32 v[104:105], v[18:19], v[104:105]
	v_cvt_pk_bf16_f32 v112, v112, v113
	v_cvt_pk_bf16_f32 v113, v104, v105
	v_mul_f32_e32 v105, v158, v249
	v_mul_f32_e32 v104, v179, v105
	v_mul_f32_e32 v115, v178, v104
	v_mul_f32_e32 v114, v175, v115
	v_mul_f32_e32 v149, v166, v247
	v_pk_mul_f32 v[114:115], v[20:21], v[114:115]
	v_pk_mul_f32 v[104:105], v[22:23], v[104:105]
	v_mul_f32_e32 v148, v189, v149
	v_cvt_pk_bf16_f32 v114, v114, v115
	v_cvt_pk_bf16_f32 v115, v104, v105
	v_mul_f32_e32 v105, v187, v148
	v_mul_f32_e32 v104, v188, v105
	v_mov_b32_e32 v150, v182
	v_mov_b32_e32 v151, v184
	v_mov_b32_e32 v184, v183
	v_cndmask_b32_e64 v156, 1.0, v156, s[34:35]
	v_pk_mul_f32 v[104:105], v[150:151], v[104:105]
	v_pk_mul_f32 v[148:149], v[184:185], v[148:149]
	v_cvt_pk_bf16_f32 v104, v104, v105
	v_cvt_pk_bf16_f32 v105, v148, v149
	v_mul_f32_e32 v149, v107, v156
	v_mul_f32_e32 v148, v243, v149
	v_mul_f32_e32 v107, v245, v148
	v_mul_f32_e32 v106, v242, v107
	v_pk_mul_f32 v[106:107], v[28:29], v[106:107]
	v_pk_mul_f32 v[148:149], v[30:31], v[148:149]
	v_add_u32_e32 v152, s53, v201
	v_cvt_pk_bf16_f32 v106, v106, v107
	v_cvt_pk_bf16_f32 v107, v148, v149
	ds_read_b64_tr_b16 v[148:149], v152 offset:16640
	ds_read_b64_tr_b16 v[150:151], v152 offset:17152
	s_waitcnt lgkmcnt(0)
	v_mfma_f32_32x32x16_bf16 v[48:63], v[238:241], v[148:151], v[48:63]
	ds_read_b64_tr_b16 v[148:149], v152 offset:20800
	ds_read_b64_tr_b16 v[150:151], v152 offset:21312
	s_waitcnt lgkmcnt(0)
	v_mfma_f32_32x32x16_bf16 v[64:79], v[238:241], v[148:151], v[64:79]
	ds_read_b64_tr_b16 v[148:149], v152 offset:17664
	ds_read_b64_tr_b16 v[150:151], v152 offset:18176
	s_waitcnt lgkmcnt(0)
	v_mfma_f32_32x32x16_bf16 v[48:63], v[108:111], v[148:151], v[48:63]
	ds_read_b64_tr_b16 v[148:149], v152 offset:21824
	ds_read_b64_tr_b16 v[150:151], v152 offset:22336
	s_waitcnt lgkmcnt(0)
	v_mfma_f32_32x32x16_bf16 v[64:79], v[108:111], v[148:151], v[64:79]
	ds_read_b64_tr_b16 v[108:109], v152 offset:18688
	ds_read_b64_tr_b16 v[110:111], v152 offset:19200
	s_waitcnt lgkmcnt(0)
	v_mfma_f32_32x32x16_bf16 v[48:63], v[112:115], v[108:111], v[48:63]
	ds_read_b64_tr_b16 v[108:109], v152 offset:22848
	ds_read_b64_tr_b16 v[110:111], v152 offset:23360
	s_waitcnt lgkmcnt(0)
	v_mfma_f32_32x32x16_bf16 v[64:79], v[112:115], v[108:111], v[64:79]
	ds_read_b64_tr_b16 v[108:109], v152 offset:19712
	ds_read_b64_tr_b16 v[110:111], v152 offset:20224
	s_waitcnt lgkmcnt(0)
	v_mfma_f32_32x32x16_bf16 v[48:63], v[104:107], v[108:111], v[48:63]
	ds_read_b64_tr_b16 v[108:109], v152 offset:23872
	ds_read_b64_tr_b16 v[110:111], v152 offset:24384
	s_waitcnt lgkmcnt(0)
	v_mfma_f32_32x32x16_bf16 v[64:79], v[104:107], v[108:111], v[64:79]
	v_mov_b32_e32 v107, v154

.LBB0_447:
	v_cmp_neq_f32_e32 vcc, 0, v107
	s_cbranch_vccz .LBB0_449
	v_add_u32_e32 v105, s53, v196
	ds_read_b128 v[0:3], v105
	ds_read_b128 v[16:19], v229 offset:60416
	v_max_f32_e64 v24, -v32, -v32
	v_min_f32_e32 v24, 0x42700000, v24
	v_exp_f32_e32 v108, v24
	s_waitcnt lgkmcnt(0)
	v_mfma_f32_32x32x16_bf16 v[0:15], v[0:3], v[16:19], 0
	ds_read_b128 v[20:23], v105 offset:512
	v_add_f32_e32 v24, 1.0, v108
	v_rcp_f32_e32 v32, v24
	v_min_f32_e64 v24, -v33, s98
	v_exp_f32_e32 v24, v24
	s_nop 0
	v_add_f32_e32 v25, 1.0, v24
	v_rcp_f32_e32 v33, v25
	s_nop 0
	v_mul_f32_e32 v104, v24, v33
	v_min_f32_e64 v24, -v34, s98
	v_exp_f32_e32 v110, v24
	s_nop 0
	v_add_f32_e32 v24, 1.0, v110
	v_rcp_f32_e32 v34, v24
	v_min_f32_e64 v24, -v35, s98
	v_exp_f32_e32 v112, v24
	s_nop 0
	v_add_f32_e32 v24, 1.0, v112
	v_rcp_f32_e32 v35, v24
	v_min_f32_e64 v36, -v36, s98
	v_min_f32_e64 v37, -v37, s98
	v_min_f32_e64 v38, -v38, s98
	v_min_f32_e64 v39, -v39, s98
	v_exp_f32_e32 v114, v36
	v_exp_f32_e32 v115, v37
	v_exp_f32_e32 v148, v38
	v_exp_f32_e32 v149, v39
	s_waitcnt lgkmcnt(0)
	v_mfma_f32_32x32x16_bf16 v[16:31], v[20:23], v[16:19], 0
	v_add_f32_e32 v36, 1.0, v114
	v_add_f32_e32 v37, 1.0, v115
	v_add_f32_e32 v38, 1.0, v148
	v_add_f32_e32 v39, 1.0, v149
	ds_read_b128 v[164:167], v105 offset:2080
	ds_read_b128 v[168:171], v229 offset:61440
	v_rcp_f32_e32 v36, v36
	v_rcp_f32_e32 v37, v37
	v_rcp_f32_e32 v38, v38
	v_rcp_f32_e32 v39, v39
	v_pk_mul_f32 v[114:115], v[114:115], v[36:37]
	s_nop 0
	v_pk_mul_f32 v[156:157], v[114:115], v[114:115] op_sel_hi:[0,1]
	v_pk_mul_f32 v[150:151], v[148:149], v[38:39]
	s_nop 0
	v_pk_mul_f32 v[154:155], v[150:151], v[150:151] op_sel_hi:[0,1]
	v_min_f32_e64 v41, -v41, s98
	s_waitcnt lgkmcnt(0)
	v_mfma_f32_32x32x16_bf16 v[0:15], v[164:167], v[168:171], v[0:15]
	v_exp_f32_e32 v164, v41
	v_min_f32_e64 v40, -v40, s98
	v_exp_f32_e32 v40, v40
	v_add_f32_e32 v41, 1.0, v164
	v_rcp_f32_e32 v152, v41
	v_min_f32_e64 v41, -v42, s98
	v_exp_f32_e32 v41, v41
	v_add_f32_e32 v106, 1.0, v40
	v_rcp_f32_e32 v148, v106
	ds_read_b128 v[172:175], v105 offset:2592
	v_add_f32_e32 v42, 1.0, v41
	v_rcp_f32_e32 v149, v42
	v_min_f32_e64 v42, -v43, s98
	v_exp_f32_e32 v165, v42
	v_pk_mul_f32 v[158:159], v[40:41], v[148:149]
	v_add_f32_e32 v42, 1.0, v165
	v_rcp_f32_e32 v153, v42
	s_nop 0
	v_pk_mul_f32 v[164:165], v[164:165], v[152:153]
	s_nop 0
	v_pk_mul_f32 v[40:41], v[158:159], v[164:165]
	s_nop 0
	v_pk_mul_f32 v[166:167], v[40:41], v[40:41] op_sel:[0,1] op_sel_hi:[1,0]
	v_min_f32_e64 v40, -v44, s98
	s_waitcnt lgkmcnt(0)
	v_mfma_f32_32x32x16_bf16 v[16:31], v[172:175], v[168:171], v[16:31]
	v_exp_f32_e32 v168, v40
	ds_read_b128 v[176:179], v105 offset:4160
	ds_read_b128 v[182:185], v229 offset:62464
	v_mov_b32_e32 v41, v152
	v_mov_b32_e32 v42, v149
	v_add_f32_e32 v40, 1.0, v168
	v_rcp_f32_e32 v44, v40
	v_min_f32_e64 v40, -v45, s98
	v_exp_f32_e32 v170, v40
	v_mov_b32_e32 v172, v44
	v_mov_b32_e32 v43, v153
	v_add_f32_e32 v40, 1.0, v170
	v_rcp_f32_e32 v45, v40
	v_min_f32_e64 v40, -v46, s98
	v_exp_f32_e32 v169, v40
	s_nop 0
	v_add_f32_e32 v40, 1.0, v169
	v_rcp_f32_e32 v46, v40
	v_min_f32_e64 v40, -v47, s98
	v_exp_f32_e32 v171, v40
	v_mov_b32_e32 v173, v46
	v_pk_mul_f32 v[168:169], v[168:169], v[172:173]
	v_mov_b32_e32 v172, v45
	v_add_f32_e32 v40, 1.0, v171
	v_rcp_f32_e32 v47, v40
	v_mov_b32_e32 v40, v148
	v_mov_b32_e32 v173, v47
	v_pk_mul_f32 v[170:171], v[170:171], v[172:173]
	s_nop 0
	v_pk_mul_f32 v[172:173], v[168:169], v[170:171]
	s_nop 0
	v_mul_f32_e32 v109, v172, v173
	v_min_f32_e64 v81, -v81, s98
	v_exp_f32_e32 v106, v81
	v_min_f32_e64 v82, -v82, s98
	v_add_f32_e32 v81, 1.0, v106
	v_rcp_f32_e32 v81, v81
	v_min_f32_e64 v80, -v80, s98
	v_min_f32_e64 v83, -v83, s98
	s_waitcnt lgkmcnt(0)
	v_mfma_f32_32x32x16_bf16 v[0:15], v[176:179], v[182:185], v[0:15]
	v_exp_f32_e32 v176, v80
	v_mul_f32_e32 v172, v106, v81
	v_exp_f32_e32 v180, v82
	v_exp_f32_e32 v106, v83
	v_add_f32_e32 v80, 1.0, v176
	ds_read_b128 v[186:189], v105 offset:4672
	v_add_f32_e32 v82, 1.0, v180
	v_add_f32_e32 v83, 1.0, v106
	v_rcp_f32_e32 v80, v80
	v_rcp_f32_e32 v82, v82
	v_rcp_f32_e32 v83, v83
	v_min_f32_e64 v84, -v84, s98
	v_min_f32_e64 v85, -v85, s98
	v_min_f32_e64 v86, -v86, s98
	v_min_f32_e64 v87, -v87, s98
	v_exp_f32_e32 v174, v84
	v_exp_f32_e32 v175, v85
	v_exp_f32_e32 v178, v86
	v_exp_f32_e32 v179, v87
	s_waitcnt lgkmcnt(0)
	v_mfma_f32_32x32x16_bf16 v[16:31], v[186:189], v[182:185], v[16:31]
	v_add_f32_e32 v84, 1.0, v174
	v_add_f32_e32 v85, 1.0, v175
	v_add_f32_e32 v86, 1.0, v178
	v_add_f32_e32 v87, 1.0, v179
	ds_read_b128 v[238:241], v105 offset:6240
	ds_read_b128 v[242:245], v229 offset:63488
	v_rcp_f32_e32 v84, v84
	v_rcp_f32_e32 v85, v85
	v_rcp_f32_e32 v86, v86
	v_rcp_f32_e32 v87, v87
	v_pk_mul_f32 v[174:175], v[174:175], v[84:85]
	s_nop 0
	v_pk_mul_f32 v[250:251], v[174:175], v[174:175] op_sel_hi:[0,1]
	v_pk_mul_f32 v[178:179], v[178:179], v[86:87]
	s_nop 0
	v_pk_mul_f32 v[252:253], v[178:179], v[178:179] op_sel_hi:[0,1]
	v_min_f32_e64 v89, -v89, s98
	v_exp_f32_e32 v188, v89
	v_min_f32_e64 v88, -v88, s98
	v_exp_f32_e32 v88, v88
	v_add_f32_e32 v89, 1.0, v188
	v_rcp_f32_e32 v184, v89
	v_min_f32_e64 v89, -v90, s98
	v_exp_f32_e32 v89, v89
	s_waitcnt lgkmcnt(0)
	v_mfma_f32_32x32x16_bf16 v[0:15], v[238:241], v[242:245], v[0:15]
	ds_read_b128 v[246:249], v105 offset:6752
	v_add_f32_e32 v105, 1.0, v88
	v_add_f32_e32 v90, 1.0, v89
	v_rcp_f32_e32 v183, v90
	v_min_f32_e64 v90, -v91, s98
	v_exp_f32_e32 v189, v90
	v_rcp_f32_e32 v182, v105
	v_add_f32_e32 v90, 1.0, v189
	v_rcp_f32_e32 v185, v90
	v_pk_mul_f32 v[186:187], v[88:89], v[182:183]
	v_pk_mul_f32 v[188:189], v[188:189], v[184:185]
	s_nop 0
	v_pk_mul_f32 v[88:89], v[186:187], v[188:189]
	s_nop 0
	v_pk_mul_f32 v[238:239], v[88:89], v[88:89] op_sel:[0,1] op_sel_hi:[1,0]
	v_min_f32_e64 v88, -v92, s98
	v_exp_f32_e32 v240, v88
	s_waitcnt lgkmcnt(0)
	v_mfma_f32_32x32x16_bf16 v[16:31], v[246:249], v[242:245], v[16:31]
	v_mov_b32_e32 v89, v184
	v_mov_b32_e32 v90, v183
	v_add_f32_e32 v88, 1.0, v240
	v_rcp_f32_e32 v92, v88
	v_min_f32_e64 v88, -v93, s98
	v_exp_f32_e32 v242, v88
	v_mov_b32_e32 v244, v92
	v_mov_b32_e32 v91, v185
	v_add_f32_e32 v88, 1.0, v242
	v_rcp_f32_e32 v93, v88
	v_min_f32_e64 v88, -v94, s98
	v_exp_f32_e32 v241, v88
	s_nop 0
	v_add_f32_e32 v88, 1.0, v241
	v_rcp_f32_e32 v94, v88
	v_min_f32_e64 v88, -v95, s98
	v_exp_f32_e32 v243, v88
	v_mov_b32_e32 v245, v94
	v_pk_mul_f32 v[244:245], v[240:241], v[244:245]
	v_mov_b32_e32 v240, v93
	v_add_f32_e32 v88, 1.0, v243
	v_rcp_f32_e32 v95, v88
	v_mov_b32_e32 v88, v182
	v_mov_b32_e32 v241, v95
	v_pk_mul_f32 v[242:243], v[242:243], v[240:241]
	s_nop 0
	v_pk_mul_f32 v[240:241], v[244:245], v[242:243]
	s_nop 0
	v_mul_f32_e32 v105, v240, v241
	v_mov_b32_e32 v111, v166
	v_mov_b32_e32 v113, v166
	s_nop 1
	v_permlane32_swap_b32_e32 v111, v113
	v_cndmask_b32_e64 v167, v111, v113, s[34:35]
	v_mov_b32_e32 v111, v109
	v_mov_b32_e32 v113, v109
	s_nop 1
	v_permlane32_swap_b32_e32 v111, v113
	v_cndmask_b32_e64 v114, v111, v113, s[34:35]
	v_mov_b32_e32 v111, v238
	v_mov_b32_e32 v113, v238
	s_nop 1
	v_permlane32_swap_b32_e32 v111, v113
	v_cndmask_b32_e64 v239, v111, v113, s[34:35]
	v_mov_b32_e32 v111, v105
	v_mov_b32_e32 v113, v105
	s_nop 1
	v_permlane32_swap_b32_e32 v111, v113
	v_mov_b32_e32 v177, v251
	v_mov_b32_e32 v252, v80
	v_cndmask_b32_e64 v156, v111, v113, s[34:35]
	v_pk_mul_f32 v[176:177], v[176:177], v[252:253]
	v_mul_f32_e32 v241, v105, v156
	v_mov_b32_e32 v105, v177
	v_mov_b32_e32 v111, v177
	s_nop 1
	v_permlane32_swap_b32_e32 v105, v111
	v_mov_b32_e32 v240, v83
	v_mov_b32_e32 v181, v238
	v_mov_b32_e32 v238, v82
	v_cndmask_b32_e64 v173, v105, v111, s[34:35]
	v_pk_mul_f32 v[246:247], v[106:107], v[240:241]
	v_pk_mul_f32 v[180:181], v[180:181], v[238:239]
	v_pk_mul_f32 v[176:177], v[176:177], v[172:173]
	v_pk_mul_f32 v[248:249], v[180:181], v[246:247]
	v_mul_f32_e32 v113, v109, v114
	v_pk_mul_f32 v[176:177], v[176:177], v[248:249]
	v_mov_b32_e32 v109, v157
	v_mov_b32_e32 v105, v176
	v_mov_b32_e32 v106, v176
	s_nop 1
	v_permlane32_swap_b32_e32 v105, v106
	v_cndmask_b32_e64 v106, v105, v106, s[34:35]
	v_mov_b32_e32 v154, v32
	v_mul_f32_e32 v105, v176, v106
	v_pk_mul_f32 v[108:109], v[108:109], v[154:155]
	v_mul_f32_e32 v251, v105, v177
	v_mov_b32_e32 v105, v109
	v_mov_b32_e32 v111, v109
	s_nop 1
	v_permlane32_swap_b32_e32 v105, v111
	v_cndmask_b32_e64 v105, v105, v111, s[34:35]
	v_mov_b32_e32 v250, v35
	v_mov_b32_e32 v111, v166
	v_mov_b32_e32 v166, v34
	v_pk_mul_f32 v[112:113], v[112:113], v[250:251]
	v_pk_mul_f32 v[110:111], v[110:111], v[166:167]
	v_pk_mul_f32 v[108:109], v[108:109], v[104:105]
	v_pk_mul_f32 v[154:155], v[110:111], v[112:113]
	v_cndmask_b32_e64 v166, 1.0, v239, s[34:35]
	v_pk_mul_f32 v[108:109], v[108:109], v[154:155]
	v_cndmask_b32_e64 v157, 1.0, v167, s[34:35]
	v_mov_b32_e32 v111, v108
	v_mov_b32_e32 v154, v108
	s_nop 1
	v_permlane32_swap_b32_e32 v111, v154
	v_cndmask_b32_e64 v111, v111, v154, s[34:35]
	v_mul_f32_e32 v108, v108, v111
	v_mul_f32_e32 v154, v108, v109
	v_cndmask_b32_e64 v108, 1.0, v111, s[34:35]
	v_mul_f32_e32 v109, v108, v109
	v_mul_f32_e32 v108, v112, v109
	v_cndmask_b32_e64 v111, 1.0, v105, s[34:35]
	v_mul_f32_e32 v105, v110, v108
	v_mul_f32_e32 v104, v104, v105
	v_pk_mul_f32 v[104:105], v[32:33], v[104:105]
	v_mov_b32_e32 v110, v148
	v_cvt_pk_bf16_f32 v238, v104, v105
	v_pk_mul_f32 v[104:105], v[34:35], v[108:109]
	v_cndmask_b32_e64 v114, 1.0, v114, s[34:35]
	v_cvt_pk_bf16_f32 v239, v104, v105
	v_mul_f32_e32 v105, v111, v155
	v_mul_f32_e32 v104, v151, v105
	v_mul_f32_e32 v109, v150, v104
	v_pk_mul_f32 v[104:105], v[38:39], v[104:105]
	v_mul_f32_e32 v108, v115, v109
	v_cvt_pk_bf16_f32 v241, v104, v105
	v_mul_f32_e32 v105, v157, v113
	v_pk_mul_f32 v[108:109], v[36:37], v[108:109]
	v_mul_f32_e32 v104, v165, v105
	v_cvt_pk_bf16_f32 v240, v108, v109
	v_mul_f32_e32 v109, v159, v104
	v_mul_f32_e32 v108, v164, v109
	v_mov_b32_e32 v111, v152
	v_mov_b32_e32 v152, v149
	v_pk_mul_f32 v[108:109], v[110:111], v[108:109]
	v_pk_mul_f32 v[104:105], v[152:153], v[104:105]
	v_cvt_pk_bf16_f32 v108, v108, v109
	v_cvt_pk_bf16_f32 v109, v104, v105
	v_mul_f32_e32 v105, v114, v251
	v_mul_f32_e32 v104, v171, v105
	v_mul_f32_e32 v111, v169, v104
	v_mul_f32_e32 v110, v170, v111
	v_cndmask_b32_e64 v106, 1.0, v106, s[34:35]
	v_pk_mul_f32 v[110:111], v[44:45], v[110:111]
	v_pk_mul_f32 v[104:105], v[46:47], v[104:105]
	v_cvt_pk_bf16_f32 v110, v110, v111
	v_cvt_pk_bf16_f32 v111, v104, v105
	v_mul_f32_e32 v105, v106, v177
	v_mul_f32_e32 v104, v246, v105
	v_mul_f32_e32 v113, v180, v104
	v_mul_f32_e32 v112, v172, v113
	v_cndmask_b32_e64 v158, 1.0, v173, s[34:35]
	v_pk_mul_f32 v[112:113], v[80:81], v[112:113]
	v_pk_mul_f32 v[104:105], v[82:83], v[104:105]
	v_cvt_pk_bf16_f32 v112, v112, v113
	v_cvt_pk_bf16_f32 v113, v104, v105
	v_mul_f32_e32 v105, v158, v249
	v_mul_f32_e32 v104, v179, v105
	v_mul_f32_e32 v115, v178, v104
	v_mul_f32_e32 v114, v175, v115
	v_mul_f32_e32 v149, v166, v247
	v_pk_mul_f32 v[114:115], v[84:85], v[114:115]
	v_pk_mul_f32 v[104:105], v[86:87], v[104:105]
	v_mul_f32_e32 v148, v189, v149
	v_cvt_pk_bf16_f32 v114, v114, v115
	v_cvt_pk_bf16_f32 v115, v104, v105
	v_mul_f32_e32 v105, v187, v148
	v_mul_f32_e32 v104, v188, v105
	v_mov_b32_e32 v150, v182
	v_mov_b32_e32 v151, v184
	v_mov_b32_e32 v184, v183
	v_cndmask_b32_e64 v156, 1.0, v156, s[34:35]
	v_pk_mul_f32 v[104:105], v[150:151], v[104:105]
	v_pk_mul_f32 v[148:149], v[184:185], v[148:149]
	v_cvt_pk_bf16_f32 v104, v104, v105
	v_cvt_pk_bf16_f32 v105, v148, v149
	v_mul_f32_e32 v149, v107, v156
	v_mul_f32_e32 v148, v243, v149
	v_mul_f32_e32 v107, v245, v148
	v_mul_f32_e32 v106, v242, v107
	v_pk_mul_f32 v[106:107], v[92:93], v[106:107]
	v_pk_mul_f32 v[148:149], v[94:95], v[148:149]
	v_cvt_pk_bf16_f32 v106, v106, v107
	v_cvt_pk_bf16_f32 v107, v148, v149
	ds_read_b64_tr_b16 v[148:149], v237 offset:16640
	ds_read_b64_tr_b16 v[150:151], v237 offset:17152
	s_waitcnt lgkmcnt(0)
	v_mfma_f32_32x32x16_bf16 v[48:63], v[238:241], v[148:151], v[48:63]
	ds_read_b64_tr_b16 v[148:149], v237 offset:20800
	ds_read_b64_tr_b16 v[150:151], v237 offset:21312
	s_waitcnt lgkmcnt(0)
	v_mfma_f32_32x32x16_bf16 v[64:79], v[238:241], v[148:151], v[64:79]
	ds_read_b64_tr_b16 v[148:149], v237 offset:17664
	ds_read_b64_tr_b16 v[150:151], v237 offset:18176
	s_waitcnt lgkmcnt(0)
	v_mfma_f32_32x32x16_bf16 v[48:63], v[108:111], v[148:151], v[48:63]
	ds_read_b64_tr_b16 v[148:149], v237 offset:21824
	ds_read_b64_tr_b16 v[150:151], v237 offset:22336
	s_waitcnt lgkmcnt(0)
	v_mfma_f32_32x32x16_bf16 v[64:79], v[108:111], v[148:151], v[64:79]
	ds_read_b64_tr_b16 v[108:109], v237 offset:18688
	ds_read_b64_tr_b16 v[110:111], v237 offset:19200
	s_waitcnt lgkmcnt(0)
	v_mfma_f32_32x32x16_bf16 v[48:63], v[112:115], v[108:111], v[48:63]
	ds_read_b64_tr_b16 v[108:109], v237 offset:22848
	ds_read_b64_tr_b16 v[110:111], v237 offset:23360
	s_waitcnt lgkmcnt(0)
	v_mfma_f32_32x32x16_bf16 v[64:79], v[112:115], v[108:111], v[64:79]
	ds_read_b64_tr_b16 v[108:109], v237 offset:19712
	ds_read_b64_tr_b16 v[110:111], v237 offset:20224
	s_waitcnt lgkmcnt(0)
	v_mfma_f32_32x32x16_bf16 v[48:63], v[104:107], v[108:111], v[48:63]
	ds_read_b64_tr_b16 v[108:109], v237 offset:23872
	ds_read_b64_tr_b16 v[110:111], v237 offset:24384
	s_waitcnt lgkmcnt(0)
	v_mfma_f32_32x32x16_bf16 v[64:79], v[104:107], v[108:111], v[64:79]
	v_mov_b32_e32 v107, v154

.LBB0_461:
	s_and_b32 s17, s22, 1
	s_mul_i32 s16, s17, 0x2080
	v_cmp_neq_f32_e32 vcc, 0, v107
	s_cbranch_vccz .LBB0_463
	v_max_f32_e64 v0, -v0, -v0
	v_min_f32_e32 v0, 0x42700000, v0
	v_exp_f32_e32 v40, v0
	v_max_f32_e64 v0, -v1, -v1
	v_min_f32_e32 v0, 0x42700000, v0
	v_exp_f32_e32 v1, v0
	v_min_f32_e64 v2, -v2, s98
	v_exp_f32_e32 v38, v2
	v_add_f32_e32 v0, 1.0, v40
	v_min_f32_e64 v2, -v3, s98
	v_rcp_f32_e32 v32, v0
	v_add_f32_e32 v0, 1.0, v1
	v_exp_f32_e32 v44, v2
	v_rcp_f32_e32 v168, v0
	v_add_f32_e32 v0, 1.0, v38
	v_rcp_f32_e32 v2, v0
	v_add_f32_e32 v0, 1.0, v44
	v_rcp_f32_e32 v0, v0
	v_mul_f32_e32 v34, v1, v168
	v_min_f32_e64 v1, -v4, s98
	v_exp_f32_e32 v36, v1
	v_min_f32_e64 v1, -v5, s98
	v_min_f32_e64 v3, -v6, s98
	v_exp_f32_e32 v37, v1
	v_exp_f32_e32 v42, v3
	v_min_f32_e64 v3, -v7, s98
	v_exp_f32_e32 v43, v3
	v_add_f32_e32 v1, 1.0, v36
	v_rcp_f32_e32 v4, v1
	v_add_f32_e32 v1, 1.0, v37
	v_rcp_f32_e32 v5, v1
	v_add_f32_e32 v1, 1.0, v42
	v_rcp_f32_e32 v6, v1
	v_add_f32_e32 v1, 1.0, v43
	v_rcp_f32_e32 v7, v1
	v_pk_mul_f32 v[36:37], v[36:37], v[4:5]
	v_pk_mul_f32 v[42:43], v[42:43], v[6:7]
	v_pk_mul_f32 v[92:93], v[36:37], v[36:37] op_sel_hi:[0,1]
	v_pk_mul_f32 v[90:91], v[42:43], v[42:43] op_sel_hi:[0,1]
	v_min_f32_e64 v1, -v8, s98
	v_exp_f32_e32 v46, v1
	v_min_f32_e64 v1, -v9, s98
	v_min_f32_e64 v3, -v10, s98
	v_exp_f32_e32 v80, v1
	v_exp_f32_e32 v47, v3
	v_min_f32_e64 v3, -v11, s98
	v_exp_f32_e32 v81, v3
	v_add_f32_e32 v1, 1.0, v46
	v_rcp_f32_e32 v8, v1
	v_add_f32_e32 v1, 1.0, v80
	v_rcp_f32_e32 v10, v1
	v_add_f32_e32 v1, 1.0, v47
	v_rcp_f32_e32 v9, v1
	v_add_f32_e32 v1, 1.0, v81
	v_rcp_f32_e32 v11, v1
	v_pk_mul_f32 v[46:47], v[46:47], v[8:9]
	v_pk_mul_f32 v[80:81], v[80:81], v[10:11]
	s_nop 0
	v_pk_mul_f32 v[82:83], v[46:47], v[80:81]
	s_nop 0
	v_pk_mul_f32 v[108:109], v[82:83], v[82:83] op_sel:[0,1] op_sel_hi:[1,0]
	v_min_f32_e64 v1, -v12, s98
	v_exp_f32_e32 v82, v1
	v_min_f32_e64 v1, -v13, s98
	v_min_f32_e64 v3, -v14, s98
	v_exp_f32_e32 v84, v1
	v_exp_f32_e32 v83, v3
	v_min_f32_e64 v3, -v15, s98
	v_exp_f32_e32 v85, v3
	v_add_f32_e32 v1, 1.0, v82
	v_rcp_f32_e32 v12, v1
	v_add_f32_e32 v1, 1.0, v84
	v_rcp_f32_e32 v14, v1
	v_add_f32_e32 v1, 1.0, v83
	v_rcp_f32_e32 v13, v1
	v_add_f32_e32 v1, 1.0, v85
	v_rcp_f32_e32 v15, v1
	v_pk_mul_f32 v[82:83], v[82:83], v[12:13]
	v_pk_mul_f32 v[84:85], v[84:85], v[14:15]
	s_nop 0
	v_pk_mul_f32 v[86:87], v[82:83], v[84:85]
	s_nop 0
	v_mul_f32_e32 v33, v86, v87
	v_min_f32_e64 v1, -v16, s98
	v_exp_f32_e32 v110, v1
	v_min_f32_e64 v1, -v17, s98
	v_exp_f32_e32 v1, v1
	v_min_f32_e64 v17, -v18, s98
	v_exp_f32_e32 v112, v17
	v_add_f32_e32 v3, 1.0, v110
	v_min_f32_e64 v17, -v19, s98
	v_rcp_f32_e32 v16, v3
	v_add_f32_e32 v3, 1.0, v1
	v_exp_f32_e32 v106, v17
	v_rcp_f32_e32 v36, v3
	v_add_f32_e32 v3, 1.0, v112
	v_rcp_f32_e32 v18, v3
	v_add_f32_e32 v3, 1.0, v106
	v_rcp_f32_e32 v86, v3
	v_mul_f32_e32 v88, v1, v36
	v_min_f32_e64 v1, -v20, s98
	v_exp_f32_e32 v94, v1
	v_min_f32_e64 v1, -v21, s98
	v_min_f32_e64 v3, -v22, s98
	v_exp_f32_e32 v95, v1
	v_exp_f32_e32 v104, v3
	v_min_f32_e64 v3, -v23, s98
	v_exp_f32_e32 v105, v3
	v_add_f32_e32 v1, 1.0, v94
	v_rcp_f32_e32 v20, v1
	v_add_f32_e32 v1, 1.0, v95
	v_rcp_f32_e32 v21, v1
	v_add_f32_e32 v1, 1.0, v104
	v_rcp_f32_e32 v22, v1
	v_add_f32_e32 v1, 1.0, v105
	v_rcp_f32_e32 v23, v1
	v_pk_mul_f32 v[94:95], v[94:95], v[20:21]
	v_pk_mul_f32 v[104:105], v[104:105], v[22:23]
	v_pk_mul_f32 v[114:115], v[94:95], v[94:95] op_sel_hi:[0,1]
	v_pk_mul_f32 v[148:149], v[104:105], v[104:105] op_sel_hi:[0,1]
	v_min_f32_e64 v1, -v24, s98
	v_exp_f32_e32 v150, v1
	v_min_f32_e64 v1, -v25, s98
	v_min_f32_e64 v3, -v26, s98
	v_exp_f32_e32 v152, v1
	v_exp_f32_e32 v151, v3
	v_min_f32_e64 v3, -v27, s98
	v_exp_f32_e32 v153, v3
	v_add_f32_e32 v1, 1.0, v150
	v_rcp_f32_e32 v24, v1
	v_add_f32_e32 v1, 1.0, v152
	v_rcp_f32_e32 v154, v1
	v_add_f32_e32 v1, 1.0, v151
	v_rcp_f32_e32 v25, v1
	v_add_f32_e32 v1, 1.0, v153
	v_rcp_f32_e32 v155, v1
	v_pk_mul_f32 v[26:27], v[150:151], v[24:25]
	v_pk_mul_f32 v[150:151], v[152:153], v[154:155]
	s_nop 0
	v_pk_mul_f32 v[152:153], v[26:27], v[150:151]
	s_nop 0
	v_pk_mul_f32 v[152:153], v[152:153], v[152:153] op_sel:[0,1] op_sel_hi:[1,0]
	v_min_f32_e64 v1, -v28, s98
	v_exp_f32_e32 v28, v1
	v_min_f32_e64 v1, -v29, s98
	v_min_f32_e64 v3, -v30, s98
	v_exp_f32_e32 v156, v1
	v_exp_f32_e32 v29, v3
	v_min_f32_e64 v3, -v31, s98
	v_exp_f32_e32 v157, v3
	v_add_f32_e32 v1, 1.0, v28
	v_rcp_f32_e32 v158, v1
	v_add_f32_e32 v1, 1.0, v156
	v_rcp_f32_e32 v164, v1
	v_add_f32_e32 v1, 1.0, v29
	v_rcp_f32_e32 v159, v1
	v_add_f32_e32 v1, 1.0, v157
	v_rcp_f32_e32 v165, v1
	v_pk_mul_f32 v[166:167], v[28:29], v[158:159]
	v_pk_mul_f32 v[156:157], v[156:157], v[164:165]
	s_nop 0
	v_pk_mul_f32 v[28:29], v[166:167], v[156:157]
	s_nop 0
	v_mul_f32_e32 v1, v28, v29
	v_mov_b32_e32 v3, v108
	v_mov_b32_e32 v17, v108
	s_nop 1
	v_permlane32_swap_b32_e32 v3, v17
	v_cndmask_b32_e64 v3, v3, v17, s[34:35]
	v_mov_b32_e32 v17, v33
	v_mov_b32_e32 v19, v33
	s_nop 1
	v_permlane32_swap_b32_e32 v17, v19
	v_cndmask_b32_e64 v46, v17, v19, s[34:35]
	v_mov_b32_e32 v17, v152
	v_mov_b32_e32 v19, v152
	s_nop 1
	v_permlane32_swap_b32_e32 v17, v19
	v_cndmask_b32_e64 v19, v17, v19, s[34:35]
	v_mov_b32_e32 v17, v1
	v_mov_b32_e32 v26, v1
	s_nop 1
	v_permlane32_swap_b32_e32 v17, v26
	v_cndmask_b32_e64 v82, v17, v26, s[34:35]
	v_mov_b32_e32 v111, v115
	v_mov_b32_e32 v17, v149
	v_pk_mul_f32 v[28:29], v[110:111], v[16:17]
	v_mul_f32_e32 v87, v1, v82
	v_mov_b32_e32 v1, v29
	v_mov_b32_e32 v17, v29
	s_nop 1
	v_permlane32_swap_b32_e32 v1, v17
	v_mov_b32_e32 v113, v152
	v_cndmask_b32_e64 v89, v1, v17, s[34:35]
	v_pk_mul_f32 v[110:111], v[106:107], v[86:87]
	v_pk_mul_f32 v[112:113], v[112:113], v[18:19]
	v_pk_mul_f32 v[28:29], v[28:29], v[88:89]
	v_pk_mul_f32 v[114:115], v[112:113], v[110:111]
	v_mul_f32_e32 v45, v33, v46
	v_pk_mul_f32 v[148:149], v[28:29], v[114:115]
	v_mov_b32_e32 v41, v93
	v_mov_b32_e32 v1, v148
	v_mov_b32_e32 v17, v148
	s_nop 1
	v_permlane32_swap_b32_e32 v1, v17
	v_mov_b32_e32 v33, v91
	v_cndmask_b32_e64 v17, v1, v17, s[34:35]
	v_pk_mul_f32 v[28:29], v[40:41], v[32:33]
	v_mul_f32_e32 v1, v148, v17
	v_mov_b32_e32 v26, v29
	v_mov_b32_e32 v30, v29
	v_mul_f32_e32 v1, v1, v149
	s_nop 0
	v_permlane32_swap_b32_e32 v26, v30
	v_mov_b32_e32 v39, v108
	v_cndmask_b32_e64 v35, v26, v30, s[34:35]
	v_pk_mul_f32 v[40:41], v[44:45], v[0:1]
	v_pk_mul_f32 v[30:31], v[38:39], v[2:3]
	v_pk_mul_f32 v[28:29], v[28:29], v[34:35]
	v_pk_mul_f32 v[38:39], v[30:31], v[40:41]
	v_mov_b32_e32 v33, v168
	v_pk_mul_f32 v[28:29], v[28:29], v[38:39]
	v_cndmask_b32_e64 v38, 1.0, v46, s[34:35]
	v_mov_b32_e32 v26, v28
	v_mov_b32_e32 v31, v28
	s_nop 1
	v_permlane32_swap_b32_e32 v26, v31
	v_cndmask_b32_e64 v31, v26, v31, s[34:35]
	v_mul_f32_e32 v26, v28, v31
	v_cndmask_b32_e64 v28, 1.0, v31, s[34:35]
	v_mul_f32_e32 v45, v28, v29
	v_mul_f32_e32 v44, v40, v45
	v_mul_f32_e32 v26, v26, v29
	v_mul_f32_e32 v29, v30, v44
	v_cndmask_b32_e64 v31, 1.0, v35, s[34:35]
	v_cndmask_b32_e64 v35, 1.0, v3, s[34:35]
	v_mul_f32_e32 v28, v34, v29
	v_mov_b32_e32 v3, v0
	v_pk_mul_f32 v[28:29], v[32:33], v[28:29]
	v_pk_mul_f32 v[2:3], v[2:3], v[44:45]
	v_cvt_pk_bf16_f32 v28, v28, v29
	v_cvt_pk_bf16_f32 v29, v2, v3
	v_mul_f32_e32 v3, v31, v39
	v_mul_f32_e32 v2, v43, v3
	v_mul_f32_e32 v31, v42, v2
	v_mul_f32_e32 v30, v37, v31
	v_pk_mul_f32 v[2:3], v[6:7], v[2:3]
	v_pk_mul_f32 v[4:5], v[4:5], v[30:31]
	v_cvt_pk_bf16_f32 v31, v2, v3
	v_mul_f32_e32 v3, v35, v41
	v_mul_f32_e32 v2, v81, v3
	v_cvt_pk_bf16_f32 v30, v4, v5
	v_mul_f32_e32 v5, v47, v2
	v_mul_f32_e32 v4, v80, v5
	v_mov_b32_e32 v6, v8
	v_mov_b32_e32 v7, v10
	v_mov_b32_e32 v10, v9
	v_mul_f32_e32 v1, v38, v1
	v_pk_mul_f32 v[4:5], v[6:7], v[4:5]
	v_pk_mul_f32 v[2:3], v[10:11], v[2:3]
	v_mul_f32_e32 v0, v85, v1
	v_cvt_pk_bf16_f32 v4, v4, v5
	v_cvt_pk_bf16_f32 v5, v2, v3
	v_mul_f32_e32 v3, v83, v0
	v_mov_b32_e32 v7, v14
	v_mov_b32_e32 v14, v13
	v_cndmask_b32_e64 v17, 1.0, v17, s[34:35]
	v_mul_f32_e32 v2, v84, v3
	v_mov_b32_e32 v6, v12
	v_pk_mul_f32 v[0:1], v[14:15], v[0:1]
	v_pk_mul_f32 v[2:3], v[6:7], v[2:3]
	v_cvt_pk_bf16_f32 v7, v0, v1
	v_mul_f32_e32 v1, v17, v149
	v_cndmask_b32_e64 v87, 1.0, v19, s[34:35]
	v_mul_f32_e32 v0, v110, v1
	v_mov_b32_e32 v19, v86
	v_cndmask_b32_e64 v46, 1.0, v89, s[34:35]
	v_cvt_pk_bf16_f32 v6, v2, v3
	v_mul_f32_e32 v3, v112, v0
	v_pk_mul_f32 v[0:1], v[18:19], v[0:1]
	v_mul_f32_e32 v2, v88, v3
	v_mov_b32_e32 v17, v36
	v_cvt_pk_bf16_f32 v9, v0, v1
	v_mul_f32_e32 v1, v46, v115
	v_pk_mul_f32 v[2:3], v[16:17], v[2:3]
	v_mul_f32_e32 v0, v105, v1
	v_cvt_pk_bf16_f32 v8, v2, v3
	v_mul_f32_e32 v3, v104, v0
	v_mul_f32_e32 v2, v95, v3
	v_pk_mul_f32 v[2:3], v[20:21], v[2:3]
	v_pk_mul_f32 v[0:1], v[22:23], v[0:1]
	v_cvt_pk_bf16_f32 v10, v2, v3
	v_mul_f32_e32 v3, v87, v111
	v_mul_f32_e32 v2, v151, v3
	v_cvt_pk_bf16_f32 v11, v0, v1
	v_mul_f32_e32 v1, v27, v2
	v_cndmask_b32_e64 v82, 1.0, v82, s[34:35]
	v_mul_f32_e32 v0, v150, v1
	v_mov_b32_e32 v12, v24
	v_mov_b32_e32 v13, v154
	v_pk_mul_f32 v[0:1], v[12:13], v[0:1]
	v_mov_b32_e32 v154, v25
	v_mul_f32_e32 v13, v107, v82
	v_pk_mul_f32 v[2:3], v[154:155], v[2:3]
	v_mul_f32_e32 v12, v157, v13
	v_cvt_pk_bf16_f32 v0, v0, v1
	v_cvt_pk_bf16_f32 v1, v2, v3
	v_mul_f32_e32 v3, v167, v12
	v_mul_f32_e32 v2, v156, v3
	v_mov_b32_e32 v14, v158
	v_mov_b32_e32 v15, v164
	v_mov_b32_e32 v164, v159
	v_pk_mul_f32 v[2:3], v[14:15], v[2:3]
	v_pk_mul_f32 v[12:13], v[164:165], v[12:13]
	v_add_u32_e32 v16, s16, v201
	v_cvt_pk_bf16_f32 v2, v2, v3
	v_cvt_pk_bf16_f32 v3, v12, v13
	ds_read_b64_tr_b16 v[12:13], v16 offset:16640
	ds_read_b64_tr_b16 v[14:15], v16 offset:17152
	s_waitcnt lgkmcnt(0)
	v_mfma_f32_32x32x16_bf16 v[48:63], v[28:31], v[12:15], v[48:63]
	ds_read_b64_tr_b16 v[12:13], v16 offset:20800
	ds_read_b64_tr_b16 v[14:15], v16 offset:21312
	v_mov_b32_e32 v107, v26
	s_waitcnt lgkmcnt(0)
	v_mfma_f32_32x32x16_bf16 v[64:79], v[28:31], v[12:15], v[64:79]
	ds_read_b64_tr_b16 v[12:13], v16 offset:17664
	ds_read_b64_tr_b16 v[14:15], v16 offset:18176
	s_waitcnt lgkmcnt(0)
	v_mfma_f32_32x32x16_bf16 v[48:63], v[4:7], v[12:15], v[48:63]
	ds_read_b64_tr_b16 v[12:13], v16 offset:21824
	ds_read_b64_tr_b16 v[14:15], v16 offset:22336
	s_waitcnt lgkmcnt(0)
	v_mfma_f32_32x32x16_bf16 v[64:79], v[4:7], v[12:15], v[64:79]
	ds_read_b64_tr_b16 v[4:5], v16 offset:18688
	ds_read_b64_tr_b16 v[6:7], v16 offset:19200
	s_waitcnt lgkmcnt(0)
	v_mfma_f32_32x32x16_bf16 v[48:63], v[8:11], v[4:7], v[48:63]
	ds_read_b64_tr_b16 v[4:5], v16 offset:22848
	ds_read_b64_tr_b16 v[6:7], v16 offset:23360
	s_waitcnt lgkmcnt(0)
	v_mfma_f32_32x32x16_bf16 v[64:79], v[8:11], v[4:7], v[64:79]
	ds_read_b64_tr_b16 v[4:5], v16 offset:19712
	ds_read_b64_tr_b16 v[6:7], v16 offset:20224
	s_waitcnt lgkmcnt(0)
	v_mfma_f32_32x32x16_bf16 v[48:63], v[0:3], v[4:7], v[48:63]
	ds_read_b64_tr_b16 v[4:5], v16 offset:23872
	ds_read_b64_tr_b16 v[6:7], v16 offset:24384
	s_waitcnt lgkmcnt(0)
	v_mfma_f32_32x32x16_bf16 v[64:79], v[0:3], v[4:7], v[64:79]
